# P4 K-loop: LDS-DMA addresses as SGPR base + 32-bit lane offset (saddr form), 16 64-bit VALU adds per iteration removed
# baseline (speedup 1.0000x reference)
.LBB0_578:
	ds_read_b128 v[72:75], v206
	ds_read_b128 v[76:79], v206 offset:1024
	ds_read_b128 v[80:83], v206 offset:2048
	ds_read_b128 v[84:87], v206 offset:3072
	ds_read_b128 v[116:119], v207
	ds_read_b128 v[120:123], v207 offset:1024
	ds_read_b128 v[124:127], v207 offset:2048
	ds_read_b128 v[128:131], v207 offset:3072
	s_add_u32 s58, s56, 0x100
	s_addc_u32 s59, s57, 0
	s_cmp_eq_u32 s79, 12
	s_cselect_b32 s63, s47, s59
	s_cselect_b32 s62, s53, s58
	s_cselect_b32 s61, s45, s78
	s_cselect_b32 s60, s76, s77
	s_add_i32 m0, s43, 0xc000
	ds_read_b128 v[140:143], v209
	ds_read_b128 v[164:167], v209 offset:1024
	ds_read_b128 v[168:171], v209 offset:2048
	ds_read_b128 v[192:195], v209 offset:3072
	ds_read_b128 v[196:199], v209 offset:4096
	ds_read_b128 v[200:203], v209 offset:5120
	ds_read_b128 v[212:215], v209 offset:6144
	ds_read_b128 v[216:219], v209 offset:7168
	global_load_lds_dwordx4 v184, s[56:57]
	s_add_i32 m0, s43, 0xe000
	s_nop 0
	global_load_lds_dwordx4 v186, s[56:57]
	s_waitcnt vmcnt(8)
	s_waitcnt lgkmcnt(0)
	s_barrier
	s_setprio 1
	s_waitcnt lgkmcnt(0)
	v_mfma_f32_16x16x32_bf16 v[160:163], v[72:75], v[140:143], v[160:163]
	v_mfma_f32_16x16x32_bf16 v[108:111], v[80:83], v[140:143], v[108:111]
	v_mfma_f32_16x16x32_bf16 v[156:159], v[72:75], v[168:171], v[156:159]
	v_mfma_f32_16x16x32_bf16 v[104:107], v[80:83], v[168:171], v[104:107]
	v_mfma_f32_16x16x32_bf16 v[144:147], v[72:75], v[196:199], v[144:147]
	v_mfma_f32_16x16x32_bf16 v[92:95], v[80:83], v[196:199], v[92:95]
	v_mfma_f32_16x16x32_bf16 v[152:155], v[72:75], v[212:215], v[152:155]
	v_mfma_f32_16x16x32_bf16 v[100:103], v[80:83], v[212:215], v[100:103]
	v_mfma_f32_16x16x32_bf16 v[160:163], v[76:79], v[164:167], v[160:163]
	v_mfma_f32_16x16x32_bf16 v[108:111], v[84:87], v[164:167], v[108:111]
	v_mfma_f32_16x16x32_bf16 v[156:159], v[76:79], v[192:195], v[156:159]
	v_mfma_f32_16x16x32_bf16 v[104:107], v[84:87], v[192:195], v[104:107]
	v_mfma_f32_16x16x32_bf16 v[144:147], v[76:79], v[200:203], v[144:147]
	v_mfma_f32_16x16x32_bf16 v[92:95], v[84:87], v[200:203], v[92:95]
	v_mfma_f32_16x16x32_bf16 v[152:155], v[76:79], v[216:219], v[152:155]
	v_mfma_f32_16x16x32_bf16 v[100:103], v[84:87], v[216:219], v[100:103]
	v_mfma_f32_16x16x32_bf16 v[148:151], v[116:119], v[140:143], v[148:151]
	v_mfma_f32_16x16x32_bf16 v[96:99], v[124:127], v[140:143], v[96:99]
	v_mfma_f32_16x16x32_bf16 v[136:139], v[116:119], v[168:171], v[136:139]
	v_mfma_f32_16x16x32_bf16 v[88:91], v[124:127], v[168:171], v[88:91]
	v_mfma_f32_16x16x32_bf16 v[132:135], v[116:119], v[196:199], v[132:135]
	v_mfma_f32_16x16x32_bf16 v[68:71], v[124:127], v[196:199], v[68:71]
	v_mfma_f32_16x16x32_bf16 v[112:115], v[116:119], v[212:215], v[112:115]
	v_mfma_f32_16x16x32_bf16 v[64:67], v[124:127], v[212:215], v[64:67]
	v_mfma_f32_16x16x32_bf16 v[148:151], v[120:123], v[164:167], v[148:151]
	v_mfma_f32_16x16x32_bf16 v[96:99], v[128:131], v[164:167], v[96:99]
	v_mfma_f32_16x16x32_bf16 v[136:139], v[120:123], v[192:195], v[136:139]
	v_mfma_f32_16x16x32_bf16 v[88:91], v[128:131], v[192:195], v[88:91]
	v_mfma_f32_16x16x32_bf16 v[132:135], v[120:123], v[200:203], v[132:135]
	v_mfma_f32_16x16x32_bf16 v[68:71], v[128:131], v[200:203], v[68:71]
	v_mfma_f32_16x16x32_bf16 v[112:115], v[120:123], v[216:219], v[112:115]
	v_mfma_f32_16x16x32_bf16 v[64:67], v[128:131], v[216:219], v[64:67]
	s_setprio 0
	s_barrier
	s_add_i32 s56, s73, s41
	s_mov_b32 m0, s56
	ds_read_b128 v[140:143], v209 offset:16384
	ds_read_b128 v[164:167], v209 offset:17408
	ds_read_b128 v[168:171], v209 offset:18432
	ds_read_b128 v[192:195], v209 offset:19456
	ds_read_b128 v[196:199], v209 offset:20480
	ds_read_b128 v[200:203], v209 offset:21504
	ds_read_b128 v[212:215], v209 offset:22528
	ds_read_b128 v[216:219], v209 offset:23552
	global_load_lds_dwordx4 v176, s[60:61]
	s_add_i32 m0, s56, 0x2000
	s_add_u32 s56, s60, 0x40000
	s_addc_u32 s57, s61, 0
	s_add_i32 s80, s74, s41
	global_load_lds_dwordx4 v180, s[60:61]
	s_mov_b32 m0, s80
	s_nop 0
	global_load_lds_dwordx4 v176, s[56:57]
	s_add_i32 m0, s80, 0x2000
	s_nop 0
	global_load_lds_dwordx4 v180, s[56:57]
	s_mov_b32 m0, s43
	s_nop 0
	global_load_lds_dwordx4 v174, s[62:63]
	s_mov_b32 m0, s55
	s_nop 0
	global_load_lds_dwordx4 v178, s[62:63]
	s_waitcnt vmcnt(8)
	s_waitcnt lgkmcnt(0)
	s_barrier
	s_setprio 1
	s_waitcnt lgkmcnt(0)
	v_mfma_f32_16x16x32_bf16 v[60:63], v[72:75], v[140:143], v[60:63]
	v_mfma_f32_16x16x32_bf16 v[28:31], v[80:83], v[140:143], v[28:31]
	v_mfma_f32_16x16x32_bf16 v[56:59], v[72:75], v[168:171], v[56:59]
	v_mfma_f32_16x16x32_bf16 v[24:27], v[80:83], v[168:171], v[24:27]
	v_mfma_f32_16x16x32_bf16 v[44:47], v[72:75], v[196:199], v[44:47]
	v_mfma_f32_16x16x32_bf16 v[12:15], v[80:83], v[196:199], v[12:15]
	v_mfma_f32_16x16x32_bf16 v[52:55], v[72:75], v[212:215], v[52:55]
	v_mfma_f32_16x16x32_bf16 v[20:23], v[80:83], v[212:215], v[20:23]
	v_mfma_f32_16x16x32_bf16 v[60:63], v[76:79], v[164:167], v[60:63]
	v_mfma_f32_16x16x32_bf16 v[28:31], v[84:87], v[164:167], v[28:31]
	v_mfma_f32_16x16x32_bf16 v[56:59], v[76:79], v[192:195], v[56:59]
	v_mfma_f32_16x16x32_bf16 v[24:27], v[84:87], v[192:195], v[24:27]
	v_mfma_f32_16x16x32_bf16 v[44:47], v[76:79], v[200:203], v[44:47]
	v_mfma_f32_16x16x32_bf16 v[12:15], v[84:87], v[200:203], v[12:15]
	v_mfma_f32_16x16x32_bf16 v[52:55], v[76:79], v[216:219], v[52:55]
	v_mfma_f32_16x16x32_bf16 v[20:23], v[84:87], v[216:219], v[20:23]
	v_mfma_f32_16x16x32_bf16 v[48:51], v[116:119], v[140:143], v[48:51]
	v_mfma_f32_16x16x32_bf16 v[16:19], v[124:127], v[140:143], v[16:19]
	v_mfma_f32_16x16x32_bf16 v[40:43], v[116:119], v[168:171], v[40:43]
	v_mfma_f32_16x16x32_bf16 v[8:11], v[124:127], v[168:171], v[8:11]
	v_mfma_f32_16x16x32_bf16 v[36:39], v[116:119], v[196:199], v[36:39]
	v_mfma_f32_16x16x32_bf16 v[4:7], v[124:127], v[196:199], v[4:7]
	v_mfma_f32_16x16x32_bf16 v[32:35], v[116:119], v[212:215], v[32:35]
	v_mfma_f32_16x16x32_bf16 v[0:3], v[124:127], v[212:215], v[0:3]
	v_mfma_f32_16x16x32_bf16 v[48:51], v[120:123], v[164:167], v[48:51]
	v_mfma_f32_16x16x32_bf16 v[16:19], v[128:131], v[164:167], v[16:19]
	v_mfma_f32_16x16x32_bf16 v[40:43], v[120:123], v[192:195], v[40:43]
	v_mfma_f32_16x16x32_bf16 v[8:11], v[128:131], v[192:195], v[8:11]
	v_mfma_f32_16x16x32_bf16 v[36:39], v[120:123], v[200:203], v[36:39]
	v_mfma_f32_16x16x32_bf16 v[4:7], v[128:131], v[200:203], v[4:7]
	v_mfma_f32_16x16x32_bf16 v[32:35], v[120:123], v[216:219], v[32:35]
	v_mfma_f32_16x16x32_bf16 v[0:3], v[128:131], v[216:219], v[0:3]
	s_setprio 0
	s_barrier
	s_add_i32 s80, 0, 0x18000
	s_add_i32 s81, 0, 0x1c000
	v_add_u32_e32 v84, s80, v204
	v_add_u32_e32 v128, s81, v204
	ds_read_b128 v[72:75], v84
	ds_read_b128 v[76:79], v84 offset:1024
	ds_read_b128 v[80:83], v84 offset:2048
	ds_read_b128 v[84:87], v84 offset:3072
	ds_read_b128 v[116:119], v128
	ds_read_b128 v[120:123], v128 offset:1024
	ds_read_b128 v[124:127], v128 offset:2048
	ds_read_b128 v[128:131], v128 offset:3072
	s_add_u32 s56, s62, 0x40000
	s_addc_u32 s57, s63, 0
	s_mov_b32 m0, s64
	ds_read_b128 v[140:143], v209 offset:32768
	ds_read_b128 v[164:167], v209 offset:33792
	ds_read_b128 v[168:171], v209 offset:34816
	ds_read_b128 v[192:195], v209 offset:35840
	ds_read_b128 v[196:199], v209 offset:36864
	ds_read_b128 v[200:203], v209 offset:37888
	ds_read_b128 v[212:215], v209 offset:38912
	ds_read_b128 v[216:219], v209 offset:39936
	global_load_lds_dwordx4 v174, s[56:57]
	s_mov_b32 m0, s65
	s_nop 0
	global_load_lds_dwordx4 v178, s[56:57]
	s_waitcnt vmcnt(8)
	s_waitcnt lgkmcnt(0)
	s_barrier
	s_setprio 1
	s_waitcnt lgkmcnt(0)
	v_mfma_f32_16x16x32_bf16 v[160:163], v[72:75], v[140:143], v[160:163]
	v_mfma_f32_16x16x32_bf16 v[108:111], v[80:83], v[140:143], v[108:111]
	v_mfma_f32_16x16x32_bf16 v[156:159], v[72:75], v[168:171], v[156:159]
	v_mfma_f32_16x16x32_bf16 v[104:107], v[80:83], v[168:171], v[104:107]
	v_mfma_f32_16x16x32_bf16 v[144:147], v[72:75], v[196:199], v[144:147]
	v_mfma_f32_16x16x32_bf16 v[92:95], v[80:83], v[196:199], v[92:95]
	v_mfma_f32_16x16x32_bf16 v[152:155], v[72:75], v[212:215], v[152:155]
	v_mfma_f32_16x16x32_bf16 v[100:103], v[80:83], v[212:215], v[100:103]
	v_mfma_f32_16x16x32_bf16 v[160:163], v[76:79], v[164:167], v[160:163]
	v_mfma_f32_16x16x32_bf16 v[108:111], v[84:87], v[164:167], v[108:111]
	v_mfma_f32_16x16x32_bf16 v[156:159], v[76:79], v[192:195], v[156:159]
	v_mfma_f32_16x16x32_bf16 v[104:107], v[84:87], v[192:195], v[104:107]
	v_mfma_f32_16x16x32_bf16 v[144:147], v[76:79], v[200:203], v[144:147]
	v_mfma_f32_16x16x32_bf16 v[92:95], v[84:87], v[200:203], v[92:95]
	v_mfma_f32_16x16x32_bf16 v[152:155], v[76:79], v[216:219], v[152:155]
	v_mfma_f32_16x16x32_bf16 v[100:103], v[84:87], v[216:219], v[100:103]
	v_mfma_f32_16x16x32_bf16 v[148:151], v[116:119], v[140:143], v[148:151]
	v_mfma_f32_16x16x32_bf16 v[96:99], v[124:127], v[140:143], v[96:99]
	v_mfma_f32_16x16x32_bf16 v[136:139], v[116:119], v[168:171], v[136:139]
	v_mfma_f32_16x16x32_bf16 v[88:91], v[124:127], v[168:171], v[88:91]
	v_mfma_f32_16x16x32_bf16 v[132:135], v[116:119], v[196:199], v[132:135]
	v_mfma_f32_16x16x32_bf16 v[68:71], v[124:127], v[196:199], v[68:71]
	v_mfma_f32_16x16x32_bf16 v[112:115], v[116:119], v[212:215], v[112:115]
	v_mfma_f32_16x16x32_bf16 v[64:67], v[124:127], v[212:215], v[64:67]
	v_mfma_f32_16x16x32_bf16 v[148:151], v[120:123], v[164:167], v[148:151]
	v_mfma_f32_16x16x32_bf16 v[96:99], v[128:131], v[164:167], v[96:99]
	v_mfma_f32_16x16x32_bf16 v[136:139], v[120:123], v[192:195], v[136:139]
	v_mfma_f32_16x16x32_bf16 v[88:91], v[128:131], v[192:195], v[88:91]
	v_mfma_f32_16x16x32_bf16 v[132:135], v[120:123], v[200:203], v[132:135]
	v_mfma_f32_16x16x32_bf16 v[68:71], v[128:131], v[200:203], v[68:71]
	v_mfma_f32_16x16x32_bf16 v[112:115], v[120:123], v[216:219], v[112:115]
	v_mfma_f32_16x16x32_bf16 v[64:67], v[128:131], v[216:219], v[64:67]
	s_setprio 0
	s_barrier
	s_add_i32 s56, s80, s41
	s_add_u32 s98, s60, s22
	s_addc_u32 s99, s61, s23
	s_add_u32 s100, s62, s22
	s_addc_u32 s101, s63, s23
	s_mov_b32 m0, s56
	ds_read_b128 v[140:143], v209 offset:49152
	ds_read_b128 v[164:167], v209 offset:50176
	ds_read_b128 v[168:171], v209 offset:51200
	ds_read_b128 v[192:195], v209 offset:52224
	ds_read_b128 v[196:199], v209 offset:53248
	ds_read_b128 v[200:203], v209 offset:54272
	ds_read_b128 v[212:215], v209 offset:55296
	ds_read_b128 v[216:219], v209 offset:56320
	global_load_lds_dwordx4 v176, s[98:99]
	s_add_i32 m0, s56, 0x2000
	s_add_u32 s56, s60, 0x40080
	s_addc_u32 s57, s61, 0
	s_add_i32 s60, s81, s41
	global_load_lds_dwordx4 v180, s[98:99]
	s_mov_b32 m0, s60
	s_nop 0
	global_load_lds_dwordx4 v176, s[56:57]
	s_add_i32 m0, s60, 0x2000
	s_nop 0
	global_load_lds_dwordx4 v180, s[56:57]
	s_mov_b32 m0, s69
	s_nop 0
	global_load_lds_dwordx4 v174, s[100:101]
	s_mov_b32 m0, s70
	s_nop 0
	global_load_lds_dwordx4 v178, s[100:101]
	s_waitcnt vmcnt(8)
	s_waitcnt lgkmcnt(0)
	s_barrier
	s_setprio 1
	s_waitcnt lgkmcnt(0)
	v_mfma_f32_16x16x32_bf16 v[60:63], v[72:75], v[140:143], v[60:63]
	v_mfma_f32_16x16x32_bf16 v[28:31], v[80:83], v[140:143], v[28:31]
	v_mfma_f32_16x16x32_bf16 v[56:59], v[72:75], v[168:171], v[56:59]
	v_mfma_f32_16x16x32_bf16 v[24:27], v[80:83], v[168:171], v[24:27]
	v_mfma_f32_16x16x32_bf16 v[44:47], v[72:75], v[196:199], v[44:47]
	v_mfma_f32_16x16x32_bf16 v[12:15], v[80:83], v[196:199], v[12:15]
	v_mfma_f32_16x16x32_bf16 v[52:55], v[72:75], v[212:215], v[52:55]
	v_mfma_f32_16x16x32_bf16 v[20:23], v[80:83], v[212:215], v[20:23]
	v_mfma_f32_16x16x32_bf16 v[60:63], v[76:79], v[164:167], v[60:63]
	v_mfma_f32_16x16x32_bf16 v[28:31], v[84:87], v[164:167], v[28:31]
	v_mfma_f32_16x16x32_bf16 v[56:59], v[76:79], v[192:195], v[56:59]
	v_mfma_f32_16x16x32_bf16 v[24:27], v[84:87], v[192:195], v[24:27]
	v_mfma_f32_16x16x32_bf16 v[44:47], v[76:79], v[200:203], v[44:47]
	v_mfma_f32_16x16x32_bf16 v[12:15], v[84:87], v[200:203], v[12:15]
	v_mfma_f32_16x16x32_bf16 v[52:55], v[76:79], v[216:219], v[52:55]
	v_mfma_f32_16x16x32_bf16 v[20:23], v[84:87], v[216:219], v[20:23]
	v_mfma_f32_16x16x32_bf16 v[48:51], v[116:119], v[140:143], v[48:51]
	v_mfma_f32_16x16x32_bf16 v[16:19], v[124:127], v[140:143], v[16:19]
	v_mfma_f32_16x16x32_bf16 v[40:43], v[116:119], v[168:171], v[40:43]
	v_mfma_f32_16x16x32_bf16 v[8:11], v[124:127], v[168:171], v[8:11]
	v_mfma_f32_16x16x32_bf16 v[36:39], v[116:119], v[196:199], v[36:39]
	v_mfma_f32_16x16x32_bf16 v[4:7], v[124:127], v[196:199], v[4:7]
	v_mfma_f32_16x16x32_bf16 v[32:35], v[116:119], v[212:215], v[32:35]
	v_mfma_f32_16x16x32_bf16 v[0:3], v[124:127], v[212:215], v[0:3]
	v_mfma_f32_16x16x32_bf16 v[48:51], v[120:123], v[164:167], v[48:51]
	v_mfma_f32_16x16x32_bf16 v[16:19], v[128:131], v[164:167], v[16:19]
	v_mfma_f32_16x16x32_bf16 v[40:43], v[120:123], v[192:195], v[40:43]
	v_mfma_f32_16x16x32_bf16 v[8:11], v[128:131], v[192:195], v[8:11]
	v_mfma_f32_16x16x32_bf16 v[36:39], v[120:123], v[200:203], v[36:39]
	v_mfma_f32_16x16x32_bf16 v[4:7], v[128:131], v[200:203], v[4:7]
	v_mfma_f32_16x16x32_bf16 v[32:35], v[120:123], v[216:219], v[32:35]
	v_mfma_f32_16x16x32_bf16 v[0:3], v[128:131], v[216:219], v[0:3]
	s_setprio 0
	s_barrier
	s_add_i32 s79, s79, 2
	s_add_u32 s77, s77, 0x100
	s_addc_u32 s78, s78, 0
	s_cmp_gt_u32 s79, 13
	s_mov_b64 s[56:57], s[58:59]
	s_cbranch_scc0 .LBB0_578
	s_and_b64 vcc, exec, s[24:25]
	s_cbranch_vccz .LBB0_581
	s_barrier

	.amdhsa_kernel _Z9hymba_fwd4Args
		.amdhsa_group_segment_fixed_size 0
		.amdhsa_private_segment_fixed_size 0
		.amdhsa_kernarg_size 440
		.amdhsa_user_sgpr_count 2
		.amdhsa_user_sgpr_dispatch_ptr 0
		.amdhsa_user_sgpr_queue_ptr 0
		.amdhsa_user_sgpr_kernarg_segment_ptr 1
		.amdhsa_user_sgpr_dispatch_id 0
		.amdhsa_user_sgpr_kernarg_preload_length 0
		.amdhsa_user_sgpr_kernarg_preload_offset 0
		.amdhsa_user_sgpr_private_segment_size 0
		.amdhsa_uses_dynamic_stack 0
		.amdhsa_enable_private_segment 0
		.amdhsa_system_sgpr_workgroup_id_x 1
		.amdhsa_system_sgpr_workgroup_id_y 0
		.amdhsa_system_sgpr_workgroup_id_z 0
		.amdhsa_system_sgpr_workgroup_info 0
		.amdhsa_system_vgpr_workitem_id 2
		.amdhsa_next_free_vgpr 255
		.amdhsa_next_free_sgpr 102
		.amdhsa_accum_offset 256
		.amdhsa_reserve_vcc 1
		.amdhsa_float_round_mode_32 0
		.amdhsa_float_round_mode_16_64 0
		.amdhsa_float_denorm_mode_32 3
		.amdhsa_float_denorm_mode_16_64 3
		.amdhsa_dx10_clamp 1
		.amdhsa_ieee_mode 1
		.amdhsa_fp16_overflow 0
		.amdhsa_tg_split 0
		.amdhsa_exception_fp_ieee_invalid_op 0
		.amdhsa_exception_fp_denorm_src 0
		.amdhsa_exception_fp_ieee_div_zero 0
		.amdhsa_exception_fp_ieee_overflow 0
		.amdhsa_exception_fp_ieee_underflow 0
		.amdhsa_exception_fp_ieee_inexact 0
		.amdhsa_exception_int_div_zero 0
	.end_amdhsa_kernel

amdhsa.kernels:
  - .agpr_count:     0
    .args:
      - .offset:         0
        .size:           184
        .value_kind:     by_value
      - .offset:         184
        .size:           4
        .value_kind:     hidden_block_count_x
      - .offset:         188
        .size:           4
        .value_kind:     hidden_block_count_y
      - .offset:         192
        .size:           4
        .value_kind:     hidden_block_count_z
      - .offset:         196
        .size:           2
        .value_kind:     hidden_group_size_x
      - .offset:         198
        .size:           2
        .value_kind:     hidden_group_size_y
      - .offset:         200
        .size:           2
        .value_kind:     hidden_group_size_z
      - .offset:         202
        .size:           2
        .value_kind:     hidden_remainder_x
      - .offset:         204
        .size:           2
        .value_kind:     hidden_remainder_y
      - .offset:         206
        .size:           2
        .value_kind:     hidden_remainder_z
      - .offset:         224
        .size:           8
        .value_kind:     hidden_global_offset_x
      - .offset:         232
        .size:           8
        .value_kind:     hidden_global_offset_y
      - .offset:         240
        .size:           8
        .value_kind:     hidden_global_offset_z
      - .offset:         248
        .size:           2
        .value_kind:     hidden_grid_dims
      - .offset:         272
        .size:           8
        .value_kind:     hidden_multigrid_sync_arg
      - .offset:         304
        .size:           4
        .value_kind:     hidden_dynamic_lds_size
    .group_segment_fixed_size: 0
    .kernarg_segment_align: 8
    .kernarg_segment_size: 440
    .language:       OpenCL C
    .language_version:
      - 2
      - 0
    .max_flat_workgroup_size: 512
    .name:           _Z9hymba_fwd4Args
    .private_segment_fixed_size: 0
    .sgpr_count:     108
    .sgpr_spill_count: 4
    .symbol:         _Z9hymba_fwd4Args.kd
    .uniform_work_group_size: 1
    .uses_dynamic_stack: false
    .vgpr_count:     255
    .vgpr_spill_count: 0
    .wavefront_size: 64
